# xcd barrier at first seam; counted waits in GLA/RWKV chunk loops; batched loads in gla_post and rwkv_post staging
# speedup vs baseline: 1.0410x; 1.0277x over previous
; __device__ __forceinline__ float bf1(bf16_t b) { return __uint_as_float(((unsigned)b) << 16); }
; __device__ __forceinline__ float sigmoid_(float x) { return __builtin_amdgcn_rcpf(1.0f + __expf(-x)); }
; __device__ __forceinline__ void st_bf(LAS bf16_t* p, float x) { *p = (bf16_t)(cvt_pk_bf16(x, x) & 0xffffu); }
; __device__ void rwkv_post_phase(const Params& p, int l, LAS unsigned char* lds) {
;     ...
;             for (int idx = tid; idx < 64 * 96; idx += 512) {
;                 const int tk = idx / 96, c = idx - tk * 96; const size_t t = t0 + tk; const int s = (int)(t & (SEQ_ - 1));
;                 const bf16_t* zp = ZR + t * ZRC + 1664 + c;
;                 const float uc = bf1(zp[0]), up_ = (s > 0) ? bf1(zp[-ZRC]) : 0.f, un = (s < SEQ_ - 1) ? bf1(zp[ZRC]) : 0.f;
;                 st_bf(sgb + tl * 6656 + tk * 104 + c, sigmoid_(uc + mu[1664 + c] * (0.5f * (up_ + un) - uc)));
;             }
.LBB0_206:
	s_or_b64 exec, exec, s[24:25]
	v_lshl_add_u64 v[2:3], v[2:3], 2, s[10:11]
	v_add_co_u32_e32 v2, vcc, 0x1000, v2
	s_nop 1
	v_addc_co_u32_e32 v3, vcc, 0, v3, vcc
	global_load_dword v2, v[2:3], off offset:2560
	s_waitcnt vmcnt(1)
	v_lshlrev_b32_e32 v10, 16, v10
	v_lshlrev_b32_e32 v5, 16, v5
	v_lshlrev_b32_e32 v6, 16, v11
	v_add_f32_e32 v3, v10, v5
	v_fma_f32 v3, v3, 0.5, -v6
	v_lshl_add_u32 v4, v4, 4, v9
	s_movk_i32 s24, 0x15ff
	v_cmp_lt_i32_e32 vcc, s24, v0
	v_add_u32_e32 v9, 0x400, v9
	s_or_b64 s[22:23], vcc, s[22:23]
	s_waitcnt vmcnt(0)
	v_fmac_f32_e32 v6, v2, v3
	v_mul_f32_e32 v2, 0xbfb8aa3b, v6
	v_exp_f32_e32 v2, v2
	s_nop 0
	v_add_f32_e32 v2, 1.0, v2
	v_rcp_f32_e32 v2, v2
	s_nop 0
	v_cvt_pk_bf16_f32 v2, v2, s0
	ds_write_b16 v4, v2
	v_add_u32_e32 v2, 0x200, v0
	v_mov_b32_e32 v0, v2
	s_andn2_b64 exec, exec, s[22:23]
	s_cbranch_execz .LBB0_203
.LBB0_207:
	s_mov_b32 s24, 0x2aaaaaab
	v_mul_hi_i32 v2, v0, s24
	v_lshrrev_b32_e32 v3, 31, v2
	v_ashrrev_i32_e32 v2, 4, v2
	v_add_u32_e32 v4, v2, v3
	v_ashrrev_i32_e32 v5, 31, v4
	s_movk_i32 s24, 0xffa0
	v_lshl_add_u64 v[6:7], s[20:21], 0, v[4:5]
	v_mov_b64_e32 v[10:11], s[4:5]
	v_mad_u64_u32 v[2:3], s[24:25], v4, s24, v[0:1]
	v_mad_u64_u32 v[10:11], s[24:25], v6, s46, v[10:11]
	v_mad_i32_i24 v11, v7, s46, v11
	v_ashrrev_i32_e32 v3, 31, v2
	v_lshl_add_u64 v[14:15], v[2:3], 1, v[10:11]
	global_load_ushort v11, v[14:15], off offset:3328
	v_and_b32_e32 v12, 0x7ff, v6
	s_mov_b64 s[24:25], 0xd00
	v_lshl_add_u64 v[6:7], v[14:15], 0, s[24:25]
	v_cmp_ne_u32_e32 vcc, 0, v12
	v_mov_b32_e32 v5, 0
	v_mov_b32_e32 v10, 0
	s_and_saveexec_b64 s[24:25], vcc
	s_cbranch_execz .LBB0_209
	v_add_co_u32_e32 v14, vcc, 0xfffff240, v6
	s_nop 1
	v_addc_co_u32_e32 v15, vcc, -1, v7, vcc
	global_load_ushort v10, v[14:15], off
.LBB0_209:
	s_or_b64 exec, exec, s[24:25]
	v_cmp_ne_u32_e32 vcc, s75, v12
	s_and_saveexec_b64 s[24:25], vcc
	s_cbranch_execz .LBB0_206
	global_load_ushort v5, v[6:7], off offset:3520
	s_branch .LBB0_206

; __device__ __forceinline__ float sigmoid_(float x) { return __builtin_amdgcn_rcpf(1.0f + __expf(-x)); }
; __device__ __forceinline__ float red16(float x) { x += __shfl_xor(x, 1); x += __shfl_xor(x, 2); x += __shfl_xor(x, 4); x += __shfl_xor(x, 8); return x; }
; __device__ __forceinline__ uint4 pack8(const float (&f)[8]) { uint4 r; r.x = cvt_pk_bf16(f[0], f[1]); r.y = cvt_pk_bf16(f[2], f[3]); r.z = cvt_pk_bf16(f[4], f[5]); r.w = cvt_pk_bf16(f[6], f[7]); return r; }
; __device__ void gla_post_phase(const Params& p, int l) {
;     ...
;     for (int idx = gtid; idx < T_ * 64; idx += gsz) {
;         const int sub = idx & 15, th = idx >> 4, h = th & 3; const size_t t = (size_t)(th >> 2); const int col = h * 128 + sub * 8;
;         float of[8], ob[8], r[8], y[8];
;         unpack8(*(const uint4*)(OF + t * 512 + col), of); unpack8(*(const uint4*)(OB + t * 512 + col), ob); unpack8(*(const uint4*)(ZG + t * ZGC + 1024 + col), r);
;         float ss = 0.f;
; #pragma unroll
;         for (int j = 0; j < 8; ++j) { of[j] += ob[j]; ss += of[j] * of[j]; }
;         ss = red16(ss);
;         const float rs = rsqrtf(ss * (1.0f / 128.0f) + 1e-6f);
; #pragma unroll
;         for (int j = 0; j < 8; ++j) y[j] = of[j] * rs * gn[col + j] * (r[j] * sigmoid_(r[j]));
;         *(uint4*)(OF + t * 512 + col) = pack8(y);
;     }
.LBB0_234:
	v_ashrrev_i32_e32 v12, 6, v2
	v_ashrrev_i32_e32 v13, 31, v12
	v_and_b32_e32 v40, 0x1f8, v7
	v_lshlrev_b64 v[14:15], 10, v[12:13]
	v_lshl_add_u64 v[8:9], s[6:7], 0, v[14:15]
	v_lshlrev_b32_e32 v0, 1, v40
	v_lshl_add_u64 v[16:17], v[8:9], 0, v[0:1]
	v_lshl_add_u64 v[44:45], s[8:9], 0, v[14:15]
	v_lshl_add_u64 v[44:45], v[44:45], 0, v[0:1]
	v_mov_b64_e32 v[48:49], s[2:3]
	v_mad_i64_i32 v[48:49], s[16:17], v12, s47, v[48:49]
	v_lshl_add_u64 v[48:49], v[48:49], 0, v[0:1]
	s_mov_b32 s16, 0x8700000
	v_add_co_u32_e32 v48, vcc, s16, v48
	s_nop 1
	v_addc_co_u32_e32 v49, vcc, 0, v49, vcc
	global_load_dwordx4 v[8:11], v[16:17], off
	global_load_dwordx4 v[44:47], v[44:45], off
	global_load_dwordx4 v[48:51], v[48:49], off offset:2048
	v_add_u32_e32 v2, s14, v2
	v_add_u32_e32 v7, s15, v7
	s_waitcnt vmcnt(2)
	v_lshlrev_b32_e32 v18, 16, v8
	v_and_b32_e32 v19, 0xffff0000, v8
	v_lshlrev_b32_e32 v20, 16, v9
	v_and_b32_e32 v21, 0xffff0000, v9
	v_lshlrev_b32_e32 v22, 16, v10
	v_and_b32_e32 v23, 0xffff0000, v10
	v_lshlrev_b32_e32 v24, 16, v11
	v_and_b32_e32 v25, 0xffff0000, v11
	s_waitcnt vmcnt(1)
	v_lshlrev_b32_e32 v26, 16, v44
	v_and_b32_e32 v27, 0xffff0000, v44
	v_lshlrev_b32_e32 v28, 16, v45
	v_and_b32_e32 v29, 0xffff0000, v45
	v_lshlrev_b32_e32 v14, 16, v46
	v_and_b32_e32 v15, 0xffff0000, v46
	v_lshlrev_b32_e32 v30, 16, v47
	v_and_b32_e32 v31, 0xffff0000, v47
	v_lshlrev_b32_e32 v0, 2, v40
	v_pk_add_f32 v[22:23], v[22:23], v[14:15]
	v_pk_add_f32 v[18:19], v[18:19], v[26:27]
	v_pk_add_f32 v[20:21], v[20:21], v[28:29]
	v_pk_mul_f32 v[26:27], v[18:19], v[18:19]
	v_pk_mul_f32 v[28:29], v[20:21], v[20:21]
	v_pk_mul_f32 v[40:41], v[22:23], v[22:23]
	v_pk_add_f32 v[24:25], v[24:25], v[30:31]
	s_waitcnt vmcnt(0)
	v_lshlrev_b32_e32 v36, 16, v50
	v_lshlrev_b32_e32 v32, 16, v48
	v_and_b32_e32 v33, 0xffff0000, v48
	v_mul_f32_e32 v8, 0xbfb8aa3b, v36
	v_exp_f32_e32 v8, v8
	v_lshlrev_b32_e32 v34, 16, v49
	v_and_b32_e32 v35, 0xffff0000, v49
	v_and_b32_e32 v37, 0xffff0000, v50
	v_add_f32_e32 v8, 1.0, v8
	v_lshlrev_b32_e32 v38, 16, v51
	v_and_b32_e32 v39, 0xffff0000, v51
	v_rcp_f32_e32 v42, v8
	global_load_dwordx4 v[8:11], v0, s[10:11] offset:16
	global_load_dwordx4 v[12:15], v0, s[10:11]
	v_mul_f32_e32 v0, 0xbfb8aa3b, v37
	v_exp_f32_e32 v0, v0
	v_pk_mul_f32 v[30:31], v[24:25], v[24:25]
	v_add_f32_e32 v0, 1.0, v0
	v_rcp_f32_e32 v43, v0
	v_mul_f32_e32 v0, 0xbfb8aa3b, v34
	v_exp_f32_e32 v0, v0
	v_pk_mul_f32 v[36:37], v[42:43], v[36:37]
	v_add_f32_e32 v0, 1.0, v0
	v_rcp_f32_e32 v42, v0
	v_mul_f32_e32 v0, 0xbfb8aa3b, v35
	v_exp_f32_e32 v0, v0
	s_nop 0
	v_add_f32_e32 v0, 1.0, v0
	v_rcp_f32_e32 v43, v0
	v_mul_f32_e32 v0, 0xbfb8aa3b, v32
	v_exp_f32_e32 v0, v0
	v_pk_mul_f32 v[34:35], v[42:43], v[34:35]
	v_add_f32_e32 v0, 1.0, v0
	v_rcp_f32_e32 v42, v0
	v_mul_f32_e32 v0, 0xbfb8aa3b, v33
	v_exp_f32_e32 v0, v0
	s_nop 0
	v_add_f32_e32 v0, 1.0, v0
	v_rcp_f32_e32 v43, v0
	v_add_f32_e32 v0, v26, v27
	v_add_f32_e32 v0, v0, v28
	v_add_f32_e32 v0, v29, v0
	v_add_f32_e32 v0, v40, v0
	v_add_f32_e32 v0, v41, v0
	v_add_f32_e32 v0, v30, v0
	v_add_f32_e32 v0, v31, v0
	ds_bpermute_b32 v26, v3, v0
	v_pk_mul_f32 v[32:33], v[42:43], v[32:33]
	s_waitcnt lgkmcnt(0)
	v_add_f32_e32 v0, v0, v26
	ds_bpermute_b32 v26, v4, v0
	s_waitcnt lgkmcnt(0)
	v_add_f32_e32 v0, v0, v26
	ds_bpermute_b32 v26, v5, v0
	s_waitcnt lgkmcnt(0)
	v_add_f32_e32 v0, v0, v26
	ds_bpermute_b32 v26, v6, v0
	s_waitcnt lgkmcnt(0)
	v_add_f32_e32 v0, v0, v26
	v_fmamk_f32 v0, v0, 0x3c000000, v169
	v_cmp_gt_f32_e32 vcc, s33, v0
	v_mul_f32_e32 v26, 0x4b800000, v0
	s_nop 0
	v_cndmask_b32_e32 v0, v0, v26, vcc
	v_rsq_f32_e32 v0, v0
	s_nop 0
	v_mul_f32_e32 v26, 0x45800000, v0
	v_cndmask_b32_e32 v0, v0, v26, vcc
	v_pk_mul_f32 v[18:19], v[18:19], v[0:1] op_sel_hi:[1,0]
	v_cmp_lt_i32_e32 vcc, s18, v2
	s_waitcnt vmcnt(0)
	v_pk_mul_f32 v[12:13], v[12:13], v[18:19]
	v_pk_mul_f32 v[18:19], v[20:21], v[0:1] op_sel_hi:[1,0]
	v_pk_mul_f32 v[20:21], v[24:25], v[0:1] op_sel_hi:[1,0]
	v_pk_mul_f32 v[14:15], v[14:15], v[18:19]
	v_pk_mul_f32 v[18:19], v[22:23], v[0:1] op_sel_hi:[1,0]
	v_mul_f32_e32 v0, 0xbfb8aa3b, v39
	v_pk_mul_f32 v[8:9], v[8:9], v[18:19]
	v_exp_f32_e32 v0, v0
	v_pk_mul_f32 v[18:19], v[36:37], v[8:9]
	v_mul_f32_e32 v8, 0xbfb8aa3b, v38
	v_exp_f32_e32 v8, v8
	v_add_f32_e32 v0, 1.0, v0
	v_rcp_f32_e32 v9, v0
	v_pk_mul_f32 v[10:11], v[10:11], v[20:21]
	v_add_f32_e32 v8, 1.0, v8
	v_rcp_f32_e32 v8, v8
	v_pk_mul_f32 v[12:13], v[32:33], v[12:13]
	v_pk_mul_f32 v[14:15], v[34:35], v[14:15]
	s_or_b64 s[12:13], vcc, s[12:13]
	v_pk_mul_f32 v[8:9], v[8:9], v[38:39]
	s_nop 0
	v_pk_mul_f32 v[20:21], v[8:9], v[10:11]
	v_cvt_pk_bf16_f32 v8, v12, v13
	v_cvt_pk_bf16_f32 v9, v14, v15
	v_cvt_pk_bf16_f32 v10, v18, v19
	v_cvt_pk_bf16_f32 v11, v20, v21
	global_store_dwordx4 v[16:17], v[8:11], off
	s_andn2_b64 exec, exec, s[12:13]
	s_cbranch_execnz .LBB0_234

; __device__ __forceinline__ void xcd_barrier(const XcdBarrier& b) {
;     asm volatile("s_waitcnt vmcnt(0)" ::: "memory");
;     __syncthreads();
;     if (threadIdx.x == 0) {
;         unsigned* bar = b.bar;
;         __builtin_amdgcn_s_waitcnt(0);
;         unsigned nloc = b.st[0], nx = b.st[1];
;         if (nloc == 0u) { xcd_barrier_complete(bar, b.x, nloc, nx); b.st[0] = nloc; b.st[1] = nx; }
; __global__ void __launch_bounds__(512, 2) fwd_kernel(Params p, int ph_lo, int ph_hi) {
;     ...
;         if (ph + 1 < ph_hi) {
;             if (ph == ph_lo) { __threadfence(); cg::this_grid().sync(); }
;             else xcd_barrier(xbar);
.LBB0_685:
	s_waitcnt vmcnt(0)
	s_waitcnt vmcnt(0)
	s_barrier
	s_mov_b64 s[2:3], exec
	v_readlane_b32 s4, v254, 5
	v_readlane_b32 s5, v254, 6
	s_and_b64 s[4:5], s[2:3], s[4:5]
	s_mov_b64 exec, s[4:5]
	s_cbranch_execz .LBB0_738
	v_readlane_b32 s4, v254, 3
	s_waitcnt vmcnt(0) expcnt(0) lgkmcnt(0)
	s_nop 0
	v_mov_b32_e32 v0, s4
	ds_read_b32 v3, v0
	v_readlane_b32 s4, v254, 4
	s_waitcnt lgkmcnt(0)
	v_cmp_ne_u32_e32 vcc, 0, v3
	v_mov_b32_e32 v0, s4
	ds_read_b32 v2, v0
	s_cbranch_vccnz .LBB0_702
	s_load_dwordx2 s[4:5], s[76:77], 0x4
	s_mov_b32 s11, 1
	s_waitcnt lgkmcnt(0)
	s_mul_i32 s10, s4, s39
	s_mul_i32 s10, s10, s5
	s_branch .LBB0_690
